# GU GEMM: per-unit next-offset lane arithmetic replaced by two per-phase VGPRs (row, column)
# speedup vs baseline: 1.0055x; 1.0055x over previous
.LBB0_1242:
	s_mov_b64 s[10:11], 0x80
	s_add_i32 m0, s28, 0x18000
	v_lshl_add_u64 v[6:7], v[6:7], 0, s[10:11]
	s_waitcnt vmcnt(2)
	s_barrier
	global_load_lds_dwordx4 v[6:7], off
	v_lshl_add_u64 v[2:3], v[2:3], 0, s[10:11]
	s_add_i32 m0, s28, 0x1a000
	s_add_i32 s38, s28, 0x8000
	s_add_i32 s39, s28, 0xa000
	global_load_lds_dwordx4 v[2:3], off
	v_lshl_add_u64 v[0:1], v[0:1], 0, s[10:11]
	s_mov_b32 m0, s38
	s_add_u32 s12, s22, 0x20080
	global_load_lds_dwordx4 v[0:1], off
	v_lshl_add_u64 v[0:1], v[4:5], 0, s[10:11]
	s_mov_b32 m0, s39
	s_addc_u32 s13, s23, 0
	global_load_lds_dwordx4 v[0:1], off
	s_add_i32 m0, s28, 0x1c000
	v_lshl_add_u64 v[0:1], s[12:13], 0, v[162:163]
	global_load_lds_dwordx4 v[0:1], off
	v_lshl_add_u64 v[0:1], s[12:13], 0, v[160:161]
	s_add_i32 m0, s28, 0x1e000
	v_and_b32_e32 v2, 48, v8
	global_load_lds_dwordx4 v[0:1], off
	v_and_b32_e32 v0, 15, v8
	v_or_b32_e32 v1, s91, v0
	v_lshlrev_b32_e32 v3, 6, v1
	s_movk_i32 s6, 0x3c0
	v_and_or_b32 v3, v3, s6, v2
	v_lshl_or_b32 v0, v0, 6, v2
	v_lshlrev_b32_e32 v2, 2, v8
	v_lshlrev_b32_e32 v1, 2, v1
	v_and_b32_e32 v2, 32, v2
	v_and_b32_e32 v1, 32, v1
	v_readlane_b32 s6, v253, 38
	v_bitop3_b32 v176, v0, s74, v2 bitop3:0xde
	s_waitcnt vmcnt(6)
	s_cmpk_lt_u32 s76, 0x100
	v_bitop3_b32 v1, v3, s6, v1 bitop3:0xde
	s_cselect_b64 s[12:13], -1, 0
	s_add_u32 s40, s66, 0x16000080
	v_add_u32_e32 v0, 0, v176
	s_mov_b32 s69, s7
	s_addc_u32 s41, s67, 0
	v_add_u32_e32 v177, 0x10000, v0
	v_add_u32_e32 v178, 0x14000, v0
	v_add_u32_e32 v179, 0, v1
	s_mov_b32 s14, 0x3d000000
	s_movk_i32 s42, 0xb00
	s_add_i32 s43, s28, 0xc000
	s_add_i32 s44, s28, 0xe000
	s_mov_b32 s45, 0
	s_barrier
	v_add_u32_e32 v247, s33, v174
	v_bfe_u32 v252, v247, 6, 1
	v_and_b32_e32 v248, 3, v247
	v_bfe_u32 v249, v247, 5, 1
	v_lshlrev_b32_e32 v248, 4, v248
	v_lshlrev_b32_e32 v249, 5, v249
	v_xor_b32_e32 v248, v248, v249
	v_lshl_add_u32 v252, v252, 6, v248
	v_lshrrev_b32_e32 v248, 7, v247
	v_bfe_u32 v247, v247, 2, 4
	v_lshl_add_u32 v247, v248, 4, v247
	s_branch .LBB0_1245

.LBB0_1247:
	s_ashr_i32 s17, s16, 31
	s_lshl_b64 s[20:21], s[16:17], 18
	s_add_u32 s20, s88, s20
	s_addc_u32 s21, s89, s21
	s_and_b64 s[24:25], s[18:19], exec
	s_cselect_b32 s17, s21, s23
	s_cselect_b32 s50, s20, s22
	s_lshl_b32 s51, s46, 8
	s_or_b32 s52, s51, 0x80
	s_add_u32 s53, s22, 0x100
	v_mov_b64_e32 v[32:33], 0
	v_mov_b64_e32 v[34:35], 0
	v_mov_b64_e32 v[36:37], 0
	v_mov_b64_e32 v[38:39], 0
	v_mov_b64_e32 v[40:41], 0
	v_mov_b64_e32 v[42:43], 0
	v_mov_b64_e32 v[44:45], 0
	v_mov_b64_e32 v[46:47], 0
	v_mov_b64_e32 v[48:49], 0
	v_mov_b64_e32 v[50:51], 0
	v_mov_b64_e32 v[52:53], 0
	v_mov_b64_e32 v[54:55], 0
	v_mov_b64_e32 v[56:57], 0
	v_mov_b64_e32 v[58:59], 0
	v_mov_b64_e32 v[60:61], 0
	v_mov_b64_e32 v[62:63], 0
	v_mov_b64_e32 v[64:65], 0
	v_mov_b64_e32 v[66:67], 0
	v_mov_b64_e32 v[68:69], 0
	v_mov_b64_e32 v[70:71], 0
	v_mov_b64_e32 v[72:73], 0
	v_mov_b64_e32 v[74:75], 0
	v_mov_b64_e32 v[76:77], 0
	v_mov_b64_e32 v[78:79], 0
	v_mov_b64_e32 v[80:81], 0
	v_mov_b64_e32 v[82:83], 0
	v_mov_b64_e32 v[84:85], 0
	v_mov_b64_e32 v[86:87], 0
	v_mov_b64_e32 v[88:89], 0
	v_mov_b64_e32 v[90:91], 0
	v_mov_b64_e32 v[92:93], 0
	v_mov_b64_e32 v[94:95], 0
	v_mov_b64_e32 v[96:97], 0
	v_mov_b64_e32 v[98:99], 0
	v_mov_b64_e32 v[100:101], 0
	v_mov_b64_e32 v[102:103], 0
	v_mov_b64_e32 v[104:105], 0
	v_mov_b64_e32 v[106:107], 0
	v_mov_b64_e32 v[108:109], 0
	v_mov_b64_e32 v[110:111], 0
	v_mov_b64_e32 v[112:113], 0
	v_mov_b64_e32 v[114:115], 0
	v_mov_b64_e32 v[116:117], 0
	v_mov_b64_e32 v[118:119], 0
	v_mov_b64_e32 v[120:121], 0
	v_mov_b64_e32 v[122:123], 0
	v_mov_b64_e32 v[124:125], 0
	v_mov_b64_e32 v[126:127], 0
	v_mov_b64_e32 v[128:129], 0
	v_mov_b64_e32 v[130:131], 0
	v_mov_b64_e32 v[132:133], 0
	v_mov_b64_e32 v[134:135], 0
	v_mov_b64_e32 v[136:137], 0
	v_mov_b64_e32 v[138:139], 0
	v_mov_b64_e32 v[140:141], 0
	v_mov_b64_e32 v[142:143], 0
	v_mov_b64_e32 v[144:145], 0
	v_mov_b64_e32 v[146:147], 0
	v_mov_b64_e32 v[148:149], 0
	v_mov_b64_e32 v[150:151], 0
	v_mov_b64_e32 v[152:153], 0
	v_mov_b64_e32 v[154:155], 0
	v_mov_b64_e32 v[156:157], 0
	v_mov_b64_e32 v[158:159], 0
	s_addc_u32 s56, s23, 0
	s_mov_b32 s57, -2
	s_mov_b64 s[22:23], 0
	s_and_b64 vcc, exec, s[18:19]
	s_cbranch_vccz .Lgu_noidx
	s_add_i32 s54, s51, 64
	s_add_i32 s55, s52, 64
	v_add_lshl_u32 v248, v247, s51, 2
	v_add_lshl_u32 v249, v247, s54, 2
	v_add_lshl_u32 v250, v247, s52, 2
	v_add_lshl_u32 v251, v247, s55, 2
	global_load_dword v248, v248, s[0:1]
	global_load_dword v249, v249, s[0:1]
	global_load_dword v250, v250, s[0:1]
	global_load_dword v251, v251, s[0:1]
.Lgu_noidx:
.LBB0_1248:
	ds_read_b128 v[16:19], v177
	ds_read_b128 v[20:23], v177 offset:1024
	ds_read_b128 v[24:27], v177 offset:2048
	ds_read_b128 v[28:31], v177 offset:3072
	ds_read_b128 v[0:3], v178
	ds_read_b128 v[4:7], v178 offset:1024
	ds_read_b128 v[8:11], v178 offset:2048
	ds_read_b128 v[12:15], v178 offset:3072
	s_cmp_eq_u32 s57, 4
	s_cselect_b64 s[26:27], -1, 0
	s_add_u32 s24, s40, s22
	s_addc_u32 s25, s41, s23
	s_mov_b32 m0, s43
	ds_read_b128 v[180:183], v179
	ds_read_b128 v[184:187], v179 offset:1024
	ds_read_b128 v[188:191], v179 offset:2048
	ds_read_b128 v[192:195], v179 offset:3072
	ds_read_b128 v[196:199], v179 offset:4096
	ds_read_b128 v[200:203], v179 offset:5120
	ds_read_b128 v[204:207], v179 offset:6144
	ds_read_b128 v[208:211], v179 offset:7168
	global_load_lds_dwordx4 v168, s[24:25]
	s_mov_b32 m0, s44
	s_nop 0
	global_load_lds_dwordx4 v166, s[24:25]
	s_waitcnt vmcnt(8)
	s_waitcnt lgkmcnt(0)
	s_barrier
	s_setprio 1
	s_waitcnt lgkmcnt(0)
	v_mfma_f32_16x16x128_f8f6f4 v[156:159], v[16:23], v[180:187], v[156:159]
	v_mfma_f32_16x16x128_f8f6f4 v[152:155], v[24:31], v[180:187], v[152:155]
	v_mfma_f32_16x16x128_f8f6f4 v[140:143], v[16:23], v[188:195], v[140:143]
	v_mfma_f32_16x16x128_f8f6f4 v[136:139], v[24:31], v[188:195], v[136:139]
	v_mfma_f32_16x16x128_f8f6f4 v[124:127], v[16:23], v[196:203], v[124:127]
	v_mfma_f32_16x16x128_f8f6f4 v[120:123], v[24:31], v[196:203], v[120:123]
	v_mfma_f32_16x16x128_f8f6f4 v[108:111], v[16:23], v[204:211], v[108:111]
	v_mfma_f32_16x16x128_f8f6f4 v[104:107], v[24:31], v[204:211], v[104:107]
	v_mfma_f32_16x16x128_f8f6f4 v[148:151], v[0:7], v[180:187], v[148:151]
	v_mfma_f32_16x16x128_f8f6f4 v[144:147], v[8:15], v[180:187], v[144:147]
	v_mfma_f32_16x16x128_f8f6f4 v[132:135], v[0:7], v[188:195], v[132:135]
	v_mfma_f32_16x16x128_f8f6f4 v[128:131], v[8:15], v[188:195], v[128:131]
	v_mfma_f32_16x16x128_f8f6f4 v[116:119], v[0:7], v[196:203], v[116:119]
	v_mfma_f32_16x16x128_f8f6f4 v[112:115], v[8:15], v[196:203], v[112:115]
	v_mfma_f32_16x16x128_f8f6f4 v[100:103], v[0:7], v[204:211], v[100:103]
	v_mfma_f32_16x16x128_f8f6f4 v[96:99], v[8:15], v[204:211], v[96:99]
	s_setprio 0
	s_barrier
	s_and_b64 s[24:25], s[18:19], s[26:27]
	s_andn2_b64 vcc, exec, s[24:25]
	s_cbranch_vccnz .LBB0_1250
	v_lshl_add_u32 v164, v248, 10, v252
	v_lshl_add_u32 v170, v249, 10, v252
	v_lshl_add_u32 v168, v250, 10, v252
	v_lshl_add_u32 v166, v251, 10, v252
	v_mov_b32_e32 v167, v165
	v_mov_b32_e32 v172, v168
	v_mov_b32_e32 v173, v165
	s_branch .LBB0_1251
